# scan loop: y dot of step t-1 deferred into step t and spread over the DPP gaps (3 independent ops per gap), rr read issued after it
# speedup vs baseline: 1.0009x; 1.0009x over previous
; #define LAS __attribute__((address_space(3)))
; __device__ __forceinline__ float sum16(float x) { x = dpp_add<0xB1>(x); x = dpp_add<0x4E>(x); x = dpp_add<0x141>(x); x = dpp_add<0x140>(x); return x; }
; __device__ __forceinline__ void scan_step(f32x4& S, const ScanOps& o, LAS float* yp) {
;     f32x2 S0 = {S[0], S[1]}, S1 = {S[2], S[3]};
;     const f32x2 k0 = {o.kk[0], o.kk[1]}, k1 = {o.kk[2], o.kk[3]};
;     f32x2 t = S0 * k0; t = S1 * k1 + t;
;     const float sa = -sum16(t[0] + t[1]);
;     const f32x2 sav = {sa, sa}, vv = {o.v, o.v};
;     const f32x2 a0 = {o.ka[0], o.ka[1]}, a1 = {o.ka[2], o.ka[3]}, p0 = {o.kp[0], o.kp[1]}, p1 = {o.kp[2], o.kp[3]}, w0 = {o.w[0], o.w[1]}, w1 = {o.w[2], o.w[3]};
;     f32x2 u0 = a0 * sav; u0 = p0 * vv + u0; S0 = S0 * w0 + u0;
;     f32x2 u1 = a1 * sav; u1 = p1 * vv + u1; S1 = S1 * w1 + u1;
;     const f32x2 r0 = {o.rr[0], o.rr[1]}, r1 = {o.rr[2], o.rr[3]};
;     f32x2 y = S0 * r0; y = S1 * r1 + y;
;     *yp = y[0] + y[1];
;     S = (f32x4){S0[0], S0[1], S1[0], S1[1]};
; }
; __device__ __forceinline__ void scan_unit(const Ctx& p, int chain, int rq, LAS unsigned char* lds) {
;     ...
;             for (int t = 0; t < SCH; t += 2) {
;                 scan_load(ob, OP, VP, t + 1);
;                 oa.v = vv[0]; ob.v = vv[1];
;                 scan_step(S, oa, Y + t * 256);
;                 scan_load(oa, OP, VP, (t + 2) & (SCH - 1));
;                 vv = *(const LAS f32x2*)(VP + ((t + 2) & (SCH - 1)));
;                 scan_step(S, ob, Y + (t + 1) * 256);
;             }
.LBB0_1714:
	s_and_b32 s12, s10, 1
	s_mulk_i32 s12, 0x5400
	s_lshl_b32 s13, s10, 14
	v_lshl_add_u32 v31, v26, 2, s12
	s_and_b32 s13, s13, 0x4000
	v_lshl_add_u32 v32, v28, 2, s12
	v_add_u32_e32 v33, s13, v29
	s_waitcnt lgkmcnt(0)
	s_barrier
	ds_read_b128 v[60:63], v31 offset:256
	ds_read_b128 v[64:67], v31 offset:768
	ds_read_b128 v[40:43], v32 offset:20480
	ds_read_b128 v[68:71], v31 offset:0
	ds_read_b128 v[72:75], v31 offset:512
	ds_read_b128 v[76:79], v31 offset:1024
	ds_read_b128 v[44:47], v32 offset:20496
	ds_read_b128 v[48:51], v32 offset:20512
	ds_read_b128 v[52:55], v32 offset:20528
	ds_read_b128 v[80:83], v31 offset:1536
	ds_read_b128 v[84:87], v31 offset:2048
	ds_read_b128 v[88:91], v31 offset:1280
	ds_read_b128 v[92:95], v31 offset:1792
	s_waitcnt lgkmcnt(12)
	v_mul_f32_e32 v100, v0, v60
	v_fmac_f32_e32 v100, v1, v61
	v_fmac_f32_e32 v100, v2, v62
	v_fmac_f32_e32 v100, v3, v63
	s_waitcnt lgkmcnt(10)
	v_mul_f32_e32 v104, v64, v40
	v_mul_f32_e32 v105, v65, v40
	v_add_f32_dpp v100, v100, v100 quad_perm:[1,0,3,2] row_mask:0xf bank_mask:0xf bound_ctrl:1
	v_mul_f32_e32 v106, v66, v40
	v_mul_f32_e32 v107, v67, v40
	v_add_f32_dpp v100, v100, v100 quad_perm:[2,3,0,1] row_mask:0xf bank_mask:0xf bound_ctrl:1
	s_waitcnt lgkmcnt(9)
	v_fmac_f32_e32 v104, v0, v68
	v_fmac_f32_e32 v105, v1, v69
	v_add_f32_dpp v100, v100, v100 row_half_mirror row_mask:0xf bank_mask:0xf bound_ctrl:1
	v_fmac_f32_e32 v106, v2, v70
	v_fmac_f32_e32 v107, v3, v71
	v_add_f32_dpp v100, v100, v100 row_mirror row_mask:0xf bank_mask:0xf bound_ctrl:1
	ds_read_b128 v[96:99], v31 offset:2304
	s_waitcnt lgkmcnt(9)
	v_fma_f32 v0, -v72, v100, v104
	v_fma_f32 v1, -v73, v100, v105
	v_fma_f32 v2, -v74, v100, v106
	v_fma_f32 v3, -v75, v100, v107
	ds_read_b128 v[60:63], v31 offset:2816
	ds_read_b128 v[64:67], v31 offset:3328
	ds_read_b128 v[68:71], v31 offset:2560
	ds_read_b128 v[72:75], v31 offset:3072
	s_waitcnt lgkmcnt(5)
	v_mul_f32_e32 v100, v0, v80
	v_fmac_f32_e32 v100, v1, v81
	v_fmac_f32_e32 v100, v2, v82
	v_fmac_f32_e32 v100, v3, v83
	v_mul_f32_e32 v104, v84, v41
	v_mul_f32_e32 v105, v85, v41
	v_mul_f32_e32 v101, v0, v76
	v_add_f32_dpp v100, v100, v100 quad_perm:[1,0,3,2] row_mask:0xf bank_mask:0xf bound_ctrl:1
	v_mul_f32_e32 v106, v86, v41
	v_mul_f32_e32 v107, v87, v41
	v_fmac_f32_e32 v101, v1, v77
	v_add_f32_dpp v100, v100, v100 quad_perm:[2,3,0,1] row_mask:0xf bank_mask:0xf bound_ctrl:1
	v_fmac_f32_e32 v104, v0, v88
	v_fmac_f32_e32 v105, v1, v89
	v_fmac_f32_e32 v101, v2, v78
	v_add_f32_dpp v100, v100, v100 row_half_mirror row_mask:0xf bank_mask:0xf bound_ctrl:1
	v_fmac_f32_e32 v106, v2, v90
	v_fmac_f32_e32 v107, v3, v91
	v_fmac_f32_e32 v101, v3, v79
	v_add_f32_dpp v100, v100, v100 row_mirror row_mask:0xf bank_mask:0xf bound_ctrl:1
	ds_write_b32 v33, v101 offset:0
	ds_read_b128 v[76:79], v31 offset:3584
	v_fma_f32 v0, -v92, v100, v104
	v_fma_f32 v1, -v93, v100, v105
	v_fma_f32 v2, -v94, v100, v106
	v_fma_f32 v3, -v95, v100, v107
	ds_read_b128 v[80:83], v31 offset:4096
	ds_read_b128 v[84:87], v31 offset:4608
	ds_read_b128 v[88:91], v31 offset:3840
	ds_read_b128 v[92:95], v31 offset:4352
	s_waitcnt lgkmcnt(6)
	v_mul_f32_e32 v100, v0, v60
	v_fmac_f32_e32 v100, v1, v61
	v_fmac_f32_e32 v100, v2, v62
	v_fmac_f32_e32 v100, v3, v63
	v_mul_f32_e32 v104, v64, v42
	v_mul_f32_e32 v105, v65, v42
	v_mul_f32_e32 v101, v0, v96
	v_add_f32_dpp v100, v100, v100 quad_perm:[1,0,3,2] row_mask:0xf bank_mask:0xf bound_ctrl:1
	v_mul_f32_e32 v106, v66, v42
	v_mul_f32_e32 v107, v67, v42
	v_fmac_f32_e32 v101, v1, v97
	v_add_f32_dpp v100, v100, v100 quad_perm:[2,3,0,1] row_mask:0xf bank_mask:0xf bound_ctrl:1
	v_fmac_f32_e32 v104, v0, v68
	v_fmac_f32_e32 v105, v1, v69
	v_fmac_f32_e32 v101, v2, v98
	v_add_f32_dpp v100, v100, v100 row_half_mirror row_mask:0xf bank_mask:0xf bound_ctrl:1
	v_fmac_f32_e32 v106, v2, v70
	v_fmac_f32_e32 v107, v3, v71
	v_fmac_f32_e32 v101, v3, v99
	v_add_f32_dpp v100, v100, v100 row_mirror row_mask:0xf bank_mask:0xf bound_ctrl:1
	ds_write_b32 v33, v101 offset:1024
	ds_read_b128 v[96:99], v31 offset:4864
	v_fma_f32 v0, -v72, v100, v104
	v_fma_f32 v1, -v73, v100, v105
	v_fma_f32 v2, -v74, v100, v106
	v_fma_f32 v3, -v75, v100, v107
	ds_read_b128 v[60:63], v31 offset:5376
	ds_read_b128 v[64:67], v31 offset:5888
	ds_read_b128 v[68:71], v31 offset:5120
	ds_read_b128 v[72:75], v31 offset:5632
	s_waitcnt lgkmcnt(6)
	v_mul_f32_e32 v100, v0, v80
	v_fmac_f32_e32 v100, v1, v81
	v_fmac_f32_e32 v100, v2, v82
	v_fmac_f32_e32 v100, v3, v83
	v_mul_f32_e32 v104, v84, v43
	v_mul_f32_e32 v105, v85, v43
	v_mul_f32_e32 v101, v0, v76
	v_add_f32_dpp v100, v100, v100 quad_perm:[1,0,3,2] row_mask:0xf bank_mask:0xf bound_ctrl:1
	v_mul_f32_e32 v106, v86, v43
	v_mul_f32_e32 v107, v87, v43
	v_fmac_f32_e32 v101, v1, v77
	v_add_f32_dpp v100, v100, v100 quad_perm:[2,3,0,1] row_mask:0xf bank_mask:0xf bound_ctrl:1
	v_fmac_f32_e32 v104, v0, v88
	v_fmac_f32_e32 v105, v1, v89
	v_fmac_f32_e32 v101, v2, v78
	v_add_f32_dpp v100, v100, v100 row_half_mirror row_mask:0xf bank_mask:0xf bound_ctrl:1
	v_fmac_f32_e32 v106, v2, v90
	v_fmac_f32_e32 v107, v3, v91
	v_fmac_f32_e32 v101, v3, v79
	v_add_f32_dpp v100, v100, v100 row_mirror row_mask:0xf bank_mask:0xf bound_ctrl:1
	ds_write_b32 v33, v101 offset:2048
	ds_read_b128 v[76:79], v31 offset:6144
	v_fma_f32 v0, -v92, v100, v104
	v_fma_f32 v1, -v93, v100, v105
	v_fma_f32 v2, -v94, v100, v106
	v_fma_f32 v3, -v95, v100, v107
	ds_read_b128 v[80:83], v31 offset:6656
	ds_read_b128 v[84:87], v31 offset:7168
	ds_read_b128 v[88:91], v31 offset:6400
	ds_read_b128 v[92:95], v31 offset:6912
	s_waitcnt lgkmcnt(6)
; #define LAS __attribute__((address_space(3)))
; __device__ __forceinline__ float sum16(float x) { x = dpp_add<0xB1>(x); x = dpp_add<0x4E>(x); x = dpp_add<0x141>(x); x = dpp_add<0x140>(x); return x; }
; __device__ __forceinline__ void scan_step(f32x4& S, const ScanOps& o, LAS float* yp) {
;     f32x2 S0 = {S[0], S[1]}, S1 = {S[2], S[3]};
;     const f32x2 k0 = {o.kk[0], o.kk[1]}, k1 = {o.kk[2], o.kk[3]};
;     f32x2 t = S0 * k0; t = S1 * k1 + t;
;     const float sa = -sum16(t[0] + t[1]);
;     const f32x2 sav = {sa, sa}, vv = {o.v, o.v};
;     const f32x2 a0 = {o.ka[0], o.ka[1]}, a1 = {o.ka[2], o.ka[3]}, p0 = {o.kp[0], o.kp[1]}, p1 = {o.kp[2], o.kp[3]}, w0 = {o.w[0], o.w[1]}, w1 = {o.w[2], o.w[3]};
;     f32x2 u0 = a0 * sav; u0 = p0 * vv + u0; S0 = S0 * w0 + u0;
;     f32x2 u1 = a1 * sav; u1 = p1 * vv + u1; S1 = S1 * w1 + u1;
;     const f32x2 r0 = {o.rr[0], o.rr[1]}, r1 = {o.rr[2], o.rr[3]};
;     f32x2 y = S0 * r0; y = S1 * r1 + y;
;     *yp = y[0] + y[1];
;     S = (f32x4){S0[0], S0[1], S1[0], S1[1]};
; }
; __device__ __forceinline__ void scan_unit(const Ctx& p, int chain, int rq, LAS unsigned char* lds) {
;     ...
;             for (int t = 0; t < SCH; t += 2) {
;                 scan_load(ob, OP, VP, t + 1);
;                 oa.v = vv[0]; ob.v = vv[1];
;                 scan_step(S, oa, Y + t * 256);
;                 scan_load(oa, OP, VP, (t + 2) & (SCH - 1));
;                 vv = *(const LAS f32x2*)(VP + ((t + 2) & (SCH - 1)));
;                 scan_step(S, ob, Y + (t + 1) * 256);
;             }
	v_mul_f32_e32 v100, v0, v60
	v_fmac_f32_e32 v100, v1, v61
	v_fmac_f32_e32 v100, v2, v62
	v_fmac_f32_e32 v100, v3, v63
	v_mul_f32_e32 v104, v64, v44
	v_mul_f32_e32 v105, v65, v44
	v_mul_f32_e32 v101, v0, v96
	v_add_f32_dpp v100, v100, v100 quad_perm:[1,0,3,2] row_mask:0xf bank_mask:0xf bound_ctrl:1
	v_mul_f32_e32 v106, v66, v44
	v_mul_f32_e32 v107, v67, v44
	v_fmac_f32_e32 v101, v1, v97
	v_add_f32_dpp v100, v100, v100 quad_perm:[2,3,0,1] row_mask:0xf bank_mask:0xf bound_ctrl:1
	v_fmac_f32_e32 v104, v0, v68
	v_fmac_f32_e32 v105, v1, v69
	v_fmac_f32_e32 v101, v2, v98
	v_add_f32_dpp v100, v100, v100 row_half_mirror row_mask:0xf bank_mask:0xf bound_ctrl:1
	v_fmac_f32_e32 v106, v2, v70
	v_fmac_f32_e32 v107, v3, v71
	v_fmac_f32_e32 v101, v3, v99
	v_add_f32_dpp v100, v100, v100 row_mirror row_mask:0xf bank_mask:0xf bound_ctrl:1
	ds_write_b32 v33, v101 offset:3072
	ds_read_b128 v[96:99], v31 offset:7424
	v_fma_f32 v0, -v72, v100, v104
	v_fma_f32 v1, -v73, v100, v105
	v_fma_f32 v2, -v74, v100, v106
	v_fma_f32 v3, -v75, v100, v107
	ds_read_b128 v[60:63], v31 offset:7936
	ds_read_b128 v[64:67], v31 offset:8448
	ds_read_b128 v[68:71], v31 offset:7680
	ds_read_b128 v[72:75], v31 offset:8192
	s_waitcnt lgkmcnt(6)
	v_mul_f32_e32 v100, v0, v80
	v_fmac_f32_e32 v100, v1, v81
	v_fmac_f32_e32 v100, v2, v82
	v_fmac_f32_e32 v100, v3, v83
	v_mul_f32_e32 v104, v84, v45
	v_mul_f32_e32 v105, v85, v45
	v_mul_f32_e32 v101, v0, v76
	v_add_f32_dpp v100, v100, v100 quad_perm:[1,0,3,2] row_mask:0xf bank_mask:0xf bound_ctrl:1
	v_mul_f32_e32 v106, v86, v45
	v_mul_f32_e32 v107, v87, v45
	v_fmac_f32_e32 v101, v1, v77
	v_add_f32_dpp v100, v100, v100 quad_perm:[2,3,0,1] row_mask:0xf bank_mask:0xf bound_ctrl:1
	v_fmac_f32_e32 v104, v0, v88
	v_fmac_f32_e32 v105, v1, v89
	v_fmac_f32_e32 v101, v2, v78
	v_add_f32_dpp v100, v100, v100 row_half_mirror row_mask:0xf bank_mask:0xf bound_ctrl:1
	v_fmac_f32_e32 v106, v2, v90
	v_fmac_f32_e32 v107, v3, v91
	v_fmac_f32_e32 v101, v3, v79
	v_add_f32_dpp v100, v100, v100 row_mirror row_mask:0xf bank_mask:0xf bound_ctrl:1
	ds_write_b32 v33, v101 offset:4096
	ds_read_b128 v[76:79], v31 offset:8704
	v_fma_f32 v0, -v92, v100, v104
	v_fma_f32 v1, -v93, v100, v105
	v_fma_f32 v2, -v94, v100, v106
	v_fma_f32 v3, -v95, v100, v107
	ds_read_b128 v[80:83], v31 offset:9216
	ds_read_b128 v[84:87], v31 offset:9728
	ds_read_b128 v[88:91], v31 offset:8960
	ds_read_b128 v[92:95], v31 offset:9472
	s_waitcnt lgkmcnt(6)
	v_mul_f32_e32 v100, v0, v60
	v_fmac_f32_e32 v100, v1, v61
	v_fmac_f32_e32 v100, v2, v62
	v_fmac_f32_e32 v100, v3, v63
	v_mul_f32_e32 v104, v64, v46
	v_mul_f32_e32 v105, v65, v46
	v_mul_f32_e32 v101, v0, v96
	v_add_f32_dpp v100, v100, v100 quad_perm:[1,0,3,2] row_mask:0xf bank_mask:0xf bound_ctrl:1
	v_mul_f32_e32 v106, v66, v46
	v_mul_f32_e32 v107, v67, v46
	v_fmac_f32_e32 v101, v1, v97
	v_add_f32_dpp v100, v100, v100 quad_perm:[2,3,0,1] row_mask:0xf bank_mask:0xf bound_ctrl:1
	v_fmac_f32_e32 v104, v0, v68
	v_fmac_f32_e32 v105, v1, v69
	v_fmac_f32_e32 v101, v2, v98
	v_add_f32_dpp v100, v100, v100 row_half_mirror row_mask:0xf bank_mask:0xf bound_ctrl:1
	v_fmac_f32_e32 v106, v2, v70
	v_fmac_f32_e32 v107, v3, v71
	v_fmac_f32_e32 v101, v3, v99
	v_add_f32_dpp v100, v100, v100 row_mirror row_mask:0xf bank_mask:0xf bound_ctrl:1
	ds_write_b32 v33, v101 offset:5120
	ds_read_b128 v[96:99], v31 offset:9984
	v_fma_f32 v0, -v72, v100, v104
	v_fma_f32 v1, -v73, v100, v105
	v_fma_f32 v2, -v74, v100, v106
	v_fma_f32 v3, -v75, v100, v107
	ds_read_b128 v[60:63], v31 offset:10496
	ds_read_b128 v[64:67], v31 offset:11008
	ds_read_b128 v[68:71], v31 offset:10240
	ds_read_b128 v[72:75], v31 offset:10752
	s_waitcnt lgkmcnt(6)
	v_mul_f32_e32 v100, v0, v80
	v_fmac_f32_e32 v100, v1, v81
	v_fmac_f32_e32 v100, v2, v82
	v_fmac_f32_e32 v100, v3, v83
	v_mul_f32_e32 v104, v84, v47
	v_mul_f32_e32 v105, v85, v47
	v_mul_f32_e32 v101, v0, v76
	v_add_f32_dpp v100, v100, v100 quad_perm:[1,0,3,2] row_mask:0xf bank_mask:0xf bound_ctrl:1
	v_mul_f32_e32 v106, v86, v47
	v_mul_f32_e32 v107, v87, v47
	v_fmac_f32_e32 v101, v1, v77
	v_add_f32_dpp v100, v100, v100 quad_perm:[2,3,0,1] row_mask:0xf bank_mask:0xf bound_ctrl:1
	v_fmac_f32_e32 v104, v0, v88
	v_fmac_f32_e32 v105, v1, v89
	v_fmac_f32_e32 v101, v2, v78
	v_add_f32_dpp v100, v100, v100 row_half_mirror row_mask:0xf bank_mask:0xf bound_ctrl:1
	v_fmac_f32_e32 v106, v2, v90
	v_fmac_f32_e32 v107, v3, v91
	v_fmac_f32_e32 v101, v3, v79
	v_add_f32_dpp v100, v100, v100 row_mirror row_mask:0xf bank_mask:0xf bound_ctrl:1
	ds_write_b32 v33, v101 offset:6144
	ds_read_b128 v[76:79], v31 offset:11264
	v_fma_f32 v0, -v92, v100, v104
	v_fma_f32 v1, -v93, v100, v105
	v_fma_f32 v2, -v94, v100, v106
	v_fma_f32 v3, -v95, v100, v107
	ds_read_b128 v[80:83], v31 offset:11776
	ds_read_b128 v[84:87], v31 offset:12288
	ds_read_b128 v[88:91], v31 offset:11520
	ds_read_b128 v[92:95], v31 offset:12032
	s_waitcnt lgkmcnt(6)
	v_mul_f32_e32 v100, v0, v60
	v_fmac_f32_e32 v100, v1, v61
	v_fmac_f32_e32 v100, v2, v62
	v_fmac_f32_e32 v100, v3, v63
	v_mul_f32_e32 v104, v64, v48
	v_mul_f32_e32 v105, v65, v48
	v_mul_f32_e32 v101, v0, v96
	v_add_f32_dpp v100, v100, v100 quad_perm:[1,0,3,2] row_mask:0xf bank_mask:0xf bound_ctrl:1
	v_mul_f32_e32 v106, v66, v48
	v_mul_f32_e32 v107, v67, v48
	v_fmac_f32_e32 v101, v1, v97
	v_add_f32_dpp v100, v100, v100 quad_perm:[2,3,0,1] row_mask:0xf bank_mask:0xf bound_ctrl:1
	v_fmac_f32_e32 v104, v0, v68
	v_fmac_f32_e32 v105, v1, v69
	v_fmac_f32_e32 v101, v2, v98
	v_add_f32_dpp v100, v100, v100 row_half_mirror row_mask:0xf bank_mask:0xf bound_ctrl:1
	v_fmac_f32_e32 v106, v2, v70
	v_fmac_f32_e32 v107, v3, v71
	v_fmac_f32_e32 v101, v3, v99
	v_add_f32_dpp v100, v100, v100 row_mirror row_mask:0xf bank_mask:0xf bound_ctrl:1
	ds_write_b32 v33, v101 offset:7168
	ds_read_b128 v[96:99], v31 offset:12544
	v_fma_f32 v0, -v72, v100, v104
	v_fma_f32 v1, -v73, v100, v105
	v_fma_f32 v2, -v74, v100, v106
	v_fma_f32 v3, -v75, v100, v107
	ds_read_b128 v[60:63], v31 offset:13056
	ds_read_b128 v[64:67], v31 offset:13568
	ds_read_b128 v[68:71], v31 offset:12800
	ds_read_b128 v[72:75], v31 offset:13312
	s_waitcnt lgkmcnt(6)
; #define LAS __attribute__((address_space(3)))
; __device__ __forceinline__ float sum16(float x) { x = dpp_add<0xB1>(x); x = dpp_add<0x4E>(x); x = dpp_add<0x141>(x); x = dpp_add<0x140>(x); return x; }
; __device__ __forceinline__ void scan_step(f32x4& S, const ScanOps& o, LAS float* yp) {
;     f32x2 S0 = {S[0], S[1]}, S1 = {S[2], S[3]};
;     const f32x2 k0 = {o.kk[0], o.kk[1]}, k1 = {o.kk[2], o.kk[3]};
;     f32x2 t = S0 * k0; t = S1 * k1 + t;
;     const float sa = -sum16(t[0] + t[1]);
;     const f32x2 sav = {sa, sa}, vv = {o.v, o.v};
;     const f32x2 a0 = {o.ka[0], o.ka[1]}, a1 = {o.ka[2], o.ka[3]}, p0 = {o.kp[0], o.kp[1]}, p1 = {o.kp[2], o.kp[3]}, w0 = {o.w[0], o.w[1]}, w1 = {o.w[2], o.w[3]};
;     f32x2 u0 = a0 * sav; u0 = p0 * vv + u0; S0 = S0 * w0 + u0;
;     f32x2 u1 = a1 * sav; u1 = p1 * vv + u1; S1 = S1 * w1 + u1;
;     const f32x2 r0 = {o.rr[0], o.rr[1]}, r1 = {o.rr[2], o.rr[3]};
;     f32x2 y = S0 * r0; y = S1 * r1 + y;
;     *yp = y[0] + y[1];
;     S = (f32x4){S0[0], S0[1], S1[0], S1[1]};
; }
; __device__ __forceinline__ void scan_unit(const Ctx& p, int chain, int rq, LAS unsigned char* lds) {
;     ...
;             for (int t = 0; t < SCH; t += 2) {
;                 scan_load(ob, OP, VP, t + 1);
;                 oa.v = vv[0]; ob.v = vv[1];
;                 scan_step(S, oa, Y + t * 256);
;                 scan_load(oa, OP, VP, (t + 2) & (SCH - 1));
;                 vv = *(const LAS f32x2*)(VP + ((t + 2) & (SCH - 1)));
;                 scan_step(S, ob, Y + (t + 1) * 256);
;             }
	v_mul_f32_e32 v100, v0, v80
	v_fmac_f32_e32 v100, v1, v81
	v_fmac_f32_e32 v100, v2, v82
	v_fmac_f32_e32 v100, v3, v83
	v_mul_f32_e32 v104, v84, v49
	v_mul_f32_e32 v105, v85, v49
	v_mul_f32_e32 v101, v0, v76
	v_add_f32_dpp v100, v100, v100 quad_perm:[1,0,3,2] row_mask:0xf bank_mask:0xf bound_ctrl:1
	v_mul_f32_e32 v106, v86, v49
	v_mul_f32_e32 v107, v87, v49
	v_fmac_f32_e32 v101, v1, v77
	v_add_f32_dpp v100, v100, v100 quad_perm:[2,3,0,1] row_mask:0xf bank_mask:0xf bound_ctrl:1
	v_fmac_f32_e32 v104, v0, v88
	v_fmac_f32_e32 v105, v1, v89
	v_fmac_f32_e32 v101, v2, v78
	v_add_f32_dpp v100, v100, v100 row_half_mirror row_mask:0xf bank_mask:0xf bound_ctrl:1
	v_fmac_f32_e32 v106, v2, v90
	v_fmac_f32_e32 v107, v3, v91
	v_fmac_f32_e32 v101, v3, v79
	v_add_f32_dpp v100, v100, v100 row_mirror row_mask:0xf bank_mask:0xf bound_ctrl:1
	ds_write_b32 v33, v101 offset:8192
	ds_read_b128 v[76:79], v31 offset:13824
	v_fma_f32 v0, -v92, v100, v104
	v_fma_f32 v1, -v93, v100, v105
	v_fma_f32 v2, -v94, v100, v106
	v_fma_f32 v3, -v95, v100, v107
	ds_read_b128 v[80:83], v31 offset:14336
	ds_read_b128 v[84:87], v31 offset:14848
	ds_read_b128 v[88:91], v31 offset:14080
	ds_read_b128 v[92:95], v31 offset:14592
	s_waitcnt lgkmcnt(6)
	v_mul_f32_e32 v100, v0, v60
	v_fmac_f32_e32 v100, v1, v61
	v_fmac_f32_e32 v100, v2, v62
	v_fmac_f32_e32 v100, v3, v63
	v_mul_f32_e32 v104, v64, v50
	v_mul_f32_e32 v105, v65, v50
	v_mul_f32_e32 v101, v0, v96
	v_add_f32_dpp v100, v100, v100 quad_perm:[1,0,3,2] row_mask:0xf bank_mask:0xf bound_ctrl:1
	v_mul_f32_e32 v106, v66, v50
	v_mul_f32_e32 v107, v67, v50
	v_fmac_f32_e32 v101, v1, v97
	v_add_f32_dpp v100, v100, v100 quad_perm:[2,3,0,1] row_mask:0xf bank_mask:0xf bound_ctrl:1
	v_fmac_f32_e32 v104, v0, v68
	v_fmac_f32_e32 v105, v1, v69
	v_fmac_f32_e32 v101, v2, v98
	v_add_f32_dpp v100, v100, v100 row_half_mirror row_mask:0xf bank_mask:0xf bound_ctrl:1
	v_fmac_f32_e32 v106, v2, v70
	v_fmac_f32_e32 v107, v3, v71
	v_fmac_f32_e32 v101, v3, v99
	v_add_f32_dpp v100, v100, v100 row_mirror row_mask:0xf bank_mask:0xf bound_ctrl:1
	ds_write_b32 v33, v101 offset:9216
	ds_read_b128 v[96:99], v31 offset:15104
	v_fma_f32 v0, -v72, v100, v104
	v_fma_f32 v1, -v73, v100, v105
	v_fma_f32 v2, -v74, v100, v106
	v_fma_f32 v3, -v75, v100, v107
	ds_read_b128 v[60:63], v31 offset:15616
	ds_read_b128 v[64:67], v31 offset:16128
	ds_read_b128 v[68:71], v31 offset:15360
	ds_read_b128 v[72:75], v31 offset:15872
	s_waitcnt lgkmcnt(6)
	v_mul_f32_e32 v100, v0, v80
	v_fmac_f32_e32 v100, v1, v81
	v_fmac_f32_e32 v100, v2, v82
	v_fmac_f32_e32 v100, v3, v83
	v_mul_f32_e32 v104, v84, v51
	v_mul_f32_e32 v105, v85, v51
	v_mul_f32_e32 v101, v0, v76
	v_add_f32_dpp v100, v100, v100 quad_perm:[1,0,3,2] row_mask:0xf bank_mask:0xf bound_ctrl:1
	v_mul_f32_e32 v106, v86, v51
	v_mul_f32_e32 v107, v87, v51
	v_fmac_f32_e32 v101, v1, v77
	v_add_f32_dpp v100, v100, v100 quad_perm:[2,3,0,1] row_mask:0xf bank_mask:0xf bound_ctrl:1
	v_fmac_f32_e32 v104, v0, v88
	v_fmac_f32_e32 v105, v1, v89
	v_fmac_f32_e32 v101, v2, v78
	v_add_f32_dpp v100, v100, v100 row_half_mirror row_mask:0xf bank_mask:0xf bound_ctrl:1
	v_fmac_f32_e32 v106, v2, v90
	v_fmac_f32_e32 v107, v3, v91
	v_fmac_f32_e32 v101, v3, v79
	v_add_f32_dpp v100, v100, v100 row_mirror row_mask:0xf bank_mask:0xf bound_ctrl:1
	ds_write_b32 v33, v101 offset:10240
	ds_read_b128 v[76:79], v31 offset:16384
	v_fma_f32 v0, -v92, v100, v104
	v_fma_f32 v1, -v93, v100, v105
	v_fma_f32 v2, -v94, v100, v106
	v_fma_f32 v3, -v95, v100, v107
	ds_read_b128 v[80:83], v31 offset:16896
	ds_read_b128 v[84:87], v31 offset:17408
	ds_read_b128 v[88:91], v31 offset:16640
	ds_read_b128 v[92:95], v31 offset:17152
	s_waitcnt lgkmcnt(6)
	v_mul_f32_e32 v100, v0, v60
	v_fmac_f32_e32 v100, v1, v61
	v_fmac_f32_e32 v100, v2, v62
	v_fmac_f32_e32 v100, v3, v63
	v_mul_f32_e32 v104, v64, v52
	v_mul_f32_e32 v105, v65, v52
	v_mul_f32_e32 v101, v0, v96
	v_add_f32_dpp v100, v100, v100 quad_perm:[1,0,3,2] row_mask:0xf bank_mask:0xf bound_ctrl:1
	v_mul_f32_e32 v106, v66, v52
	v_mul_f32_e32 v107, v67, v52
	v_fmac_f32_e32 v101, v1, v97
	v_add_f32_dpp v100, v100, v100 quad_perm:[2,3,0,1] row_mask:0xf bank_mask:0xf bound_ctrl:1
	v_fmac_f32_e32 v104, v0, v68
	v_fmac_f32_e32 v105, v1, v69
	v_fmac_f32_e32 v101, v2, v98
	v_add_f32_dpp v100, v100, v100 row_half_mirror row_mask:0xf bank_mask:0xf bound_ctrl:1
	v_fmac_f32_e32 v106, v2, v70
	v_fmac_f32_e32 v107, v3, v71
	v_fmac_f32_e32 v101, v3, v99
	v_add_f32_dpp v100, v100, v100 row_mirror row_mask:0xf bank_mask:0xf bound_ctrl:1
	ds_write_b32 v33, v101 offset:11264
	ds_read_b128 v[96:99], v31 offset:17664
	v_fma_f32 v0, -v72, v100, v104
	v_fma_f32 v1, -v73, v100, v105
	v_fma_f32 v2, -v74, v100, v106
	v_fma_f32 v3, -v75, v100, v107
	ds_read_b128 v[60:63], v31 offset:18176
	ds_read_b128 v[64:67], v31 offset:18688
	ds_read_b128 v[68:71], v31 offset:17920
	ds_read_b128 v[72:75], v31 offset:18432
	s_waitcnt lgkmcnt(6)
; #define LAS __attribute__((address_space(3)))
; __device__ __forceinline__ float sum16(float x) { x = dpp_add<0xB1>(x); x = dpp_add<0x4E>(x); x = dpp_add<0x141>(x); x = dpp_add<0x140>(x); return x; }
; __device__ __forceinline__ void scan_step(f32x4& S, const ScanOps& o, LAS float* yp) {
;     f32x2 S0 = {S[0], S[1]}, S1 = {S[2], S[3]};
;     const f32x2 k0 = {o.kk[0], o.kk[1]}, k1 = {o.kk[2], o.kk[3]};
;     f32x2 t = S0 * k0; t = S1 * k1 + t;
;     const float sa = -sum16(t[0] + t[1]);
;     const f32x2 sav = {sa, sa}, vv = {o.v, o.v};
;     const f32x2 a0 = {o.ka[0], o.ka[1]}, a1 = {o.ka[2], o.ka[3]}, p0 = {o.kp[0], o.kp[1]}, p1 = {o.kp[2], o.kp[3]}, w0 = {o.w[0], o.w[1]}, w1 = {o.w[2], o.w[3]};
;     f32x2 u0 = a0 * sav; u0 = p0 * vv + u0; S0 = S0 * w0 + u0;
;     f32x2 u1 = a1 * sav; u1 = p1 * vv + u1; S1 = S1 * w1 + u1;
;     const f32x2 r0 = {o.rr[0], o.rr[1]}, r1 = {o.rr[2], o.rr[3]};
;     f32x2 y = S0 * r0; y = S1 * r1 + y;
;     *yp = y[0] + y[1];
;     S = (f32x4){S0[0], S0[1], S1[0], S1[1]};
; }
; __device__ __forceinline__ void scan_unit(const Ctx& p, int chain, int rq, LAS unsigned char* lds) {
;     ...
;             for (int t = 0; t < SCH; t += 2) {
;                 scan_load(ob, OP, VP, t + 1);
;                 oa.v = vv[0]; ob.v = vv[1];
;                 scan_step(S, oa, Y + t * 256);
;                 scan_load(oa, OP, VP, (t + 2) & (SCH - 1));
;                 vv = *(const LAS f32x2*)(VP + ((t + 2) & (SCH - 1)));
;                 scan_step(S, ob, Y + (t + 1) * 256);
;             }
;         }
;         __syncthreads();
;         *(f32x4*)sg = S;
	v_mul_f32_e32 v100, v0, v80
	v_fmac_f32_e32 v100, v1, v81
	v_fmac_f32_e32 v100, v2, v82
	v_fmac_f32_e32 v100, v3, v83
	v_mul_f32_e32 v104, v84, v53
	v_mul_f32_e32 v105, v85, v53
	v_mul_f32_e32 v101, v0, v76
	v_add_f32_dpp v100, v100, v100 quad_perm:[1,0,3,2] row_mask:0xf bank_mask:0xf bound_ctrl:1
	v_mul_f32_e32 v106, v86, v53
	v_mul_f32_e32 v107, v87, v53
	v_fmac_f32_e32 v101, v1, v77
	v_add_f32_dpp v100, v100, v100 quad_perm:[2,3,0,1] row_mask:0xf bank_mask:0xf bound_ctrl:1
	v_fmac_f32_e32 v104, v0, v88
	v_fmac_f32_e32 v105, v1, v89
	v_fmac_f32_e32 v101, v2, v78
	v_add_f32_dpp v100, v100, v100 row_half_mirror row_mask:0xf bank_mask:0xf bound_ctrl:1
	v_fmac_f32_e32 v106, v2, v90
	v_fmac_f32_e32 v107, v3, v91
	v_fmac_f32_e32 v101, v3, v79
	v_add_f32_dpp v100, v100, v100 row_mirror row_mask:0xf bank_mask:0xf bound_ctrl:1
	ds_write_b32 v33, v101 offset:12288
	ds_read_b128 v[76:79], v31 offset:18944
	v_fma_f32 v0, -v92, v100, v104
	v_fma_f32 v1, -v93, v100, v105
	v_fma_f32 v2, -v94, v100, v106
	v_fma_f32 v3, -v95, v100, v107
	ds_read_b128 v[80:83], v31 offset:19456
	ds_read_b128 v[84:87], v31 offset:19968
	ds_read_b128 v[88:91], v31 offset:19200
	ds_read_b128 v[92:95], v31 offset:19712
	s_waitcnt lgkmcnt(6)
	v_mul_f32_e32 v100, v0, v60
	v_fmac_f32_e32 v100, v1, v61
	v_fmac_f32_e32 v100, v2, v62
	v_fmac_f32_e32 v100, v3, v63
	v_mul_f32_e32 v104, v64, v54
	v_mul_f32_e32 v105, v65, v54
	v_mul_f32_e32 v101, v0, v96
	v_add_f32_dpp v100, v100, v100 quad_perm:[1,0,3,2] row_mask:0xf bank_mask:0xf bound_ctrl:1
	v_mul_f32_e32 v106, v66, v54
	v_mul_f32_e32 v107, v67, v54
	v_fmac_f32_e32 v101, v1, v97
	v_add_f32_dpp v100, v100, v100 quad_perm:[2,3,0,1] row_mask:0xf bank_mask:0xf bound_ctrl:1
	v_fmac_f32_e32 v104, v0, v68
	v_fmac_f32_e32 v105, v1, v69
	v_fmac_f32_e32 v101, v2, v98
	v_add_f32_dpp v100, v100, v100 row_half_mirror row_mask:0xf bank_mask:0xf bound_ctrl:1
	v_fmac_f32_e32 v106, v2, v70
	v_fmac_f32_e32 v107, v3, v71
	v_fmac_f32_e32 v101, v3, v99
	v_add_f32_dpp v100, v100, v100 row_mirror row_mask:0xf bank_mask:0xf bound_ctrl:1
	ds_write_b32 v33, v101 offset:13312
	ds_read_b128 v[96:99], v31 offset:20224
	v_fma_f32 v0, -v72, v100, v104
	v_fma_f32 v1, -v73, v100, v105
	v_fma_f32 v2, -v74, v100, v106
	v_fma_f32 v3, -v75, v100, v107
	s_waitcnt lgkmcnt(2)
	v_mul_f32_e32 v100, v0, v80
	v_fmac_f32_e32 v100, v1, v81
	v_fmac_f32_e32 v100, v2, v82
	v_fmac_f32_e32 v100, v3, v83
	v_mul_f32_e32 v104, v84, v55
	v_mul_f32_e32 v105, v85, v55
	v_mul_f32_e32 v101, v0, v76
	v_add_f32_dpp v100, v100, v100 quad_perm:[1,0,3,2] row_mask:0xf bank_mask:0xf bound_ctrl:1
	v_mul_f32_e32 v106, v86, v55
	v_mul_f32_e32 v107, v87, v55
	v_fmac_f32_e32 v101, v1, v77
	v_add_f32_dpp v100, v100, v100 quad_perm:[2,3,0,1] row_mask:0xf bank_mask:0xf bound_ctrl:1
	v_fmac_f32_e32 v104, v0, v88
	v_fmac_f32_e32 v105, v1, v89
	v_fmac_f32_e32 v101, v2, v78
	v_add_f32_dpp v100, v100, v100 row_half_mirror row_mask:0xf bank_mask:0xf bound_ctrl:1
	v_fmac_f32_e32 v106, v2, v90
	v_fmac_f32_e32 v107, v3, v91
	v_fmac_f32_e32 v101, v3, v79
	v_add_f32_dpp v100, v100, v100 row_mirror row_mask:0xf bank_mask:0xf bound_ctrl:1
	ds_write_b32 v33, v101 offset:14336
	v_fma_f32 v0, -v92, v100, v104
	v_fma_f32 v1, -v93, v100, v105
	v_fma_f32 v2, -v94, v100, v106
	v_fma_f32 v3, -v95, v100, v107
	s_waitcnt lgkmcnt(1)
	v_mul_f32_e32 v101, v0, v96
	v_fmac_f32_e32 v101, v1, v97
	v_fmac_f32_e32 v101, v2, v98
	v_fmac_f32_e32 v101, v3, v99
	ds_write_b32 v33, v101 offset:15360
	s_add_i32 s10, s10, 1
	s_cmpk_eq_i32 s10, 0x100
	s_cbranch_scc0 .LBB0_1714
	s_setprio 0
	s_lshl_b32 s8, s28, 12
	v_lshl_or_b32 v4, v27, 8, s8
	v_mov_b32_e32 v5, 0
	v_lshl_add_u64 v[6:7], s[2:3], 0, v[4:5]
	v_lshlrev_b32_e32 v4, 2, v26
	v_lshl_add_u64 v[4:5], v[6:7], 0, v[4:5]
	v_add_co_u32_e32 v4, vcc, 0x8080000, v4
	s_mov_b64 s[2:3], 0
	s_nop 0
	v_addc_co_u32_e32 v5, vcc, 0, v5, vcc
	s_waitcnt lgkmcnt(0)
	s_barrier
	global_store_dwordx4 v[4:5], v[0:3], off
